# conversion seam allocation 0,1,2,5x2,6x2 (one item moved from seam 1 to the idle waves of seam 0) on v226
# speedup vs baseline: 1.0044x; 1.0023x over previous
.Lmy_cv0_go:
	s_add_u32 s20, s50, s20
	s_addc_u32 s21, s51, 0
	v_and_b32_e32 v2, 7, v1
	v_lshrrev_b32_e32 v3, 3, v1
	s_lshl_b32 s24, s15, 6
	v_lshl_add_u32 v4, v2, 3, s24
	v_mul_lo_u32 v4, v4, s19
	v_lshl_add_u32 v5, v3, 2, s31
	v_add_u32_e32 v4, v4, v5
	v_mov_b32_e32 v5, 0
	v_lshlrev_b64 v[4:5], 2, v[4:5]
	s_lshl_b32 s26, s19, 2
	s_mov_b32 s27, 0
	s_lshr_b32 s28, s18, 8
	s_and_b32 s29, s18, 0xff
	s_lshl_b32 s28, s28, 5
	s_add_u32 s28, s28, s15
	s_lshl_b32 s28, s28, 8
	s_add_u32 s28, s28, s29
	s_waitcnt lgkmcnt(0)
	v_lshl_add_u64 v[4:5], s[12:13], 0, v[4:5]
	global_load_dwordx4 v[8:11], v[4:5], off nt
	v_lshl_add_u64 v[4:5], v[4:5], 0, s[26:27]
	global_load_dwordx4 v[12:15], v[4:5], off nt
	v_lshl_add_u64 v[4:5], v[4:5], 0, s[26:27]
	global_load_dwordx4 v[16:19], v[4:5], off nt
	v_lshl_add_u64 v[4:5], v[4:5], 0, s[26:27]
	global_load_dwordx4 v[20:23], v[4:5], off nt
	v_lshl_add_u64 v[4:5], v[4:5], 0, s[26:27]
	global_load_dwordx4 v[24:27], v[4:5], off nt
	v_lshl_add_u64 v[4:5], v[4:5], 0, s[26:27]
	global_load_dwordx4 v[28:31], v[4:5], off nt
	v_lshl_add_u64 v[4:5], v[4:5], 0, s[26:27]
	global_load_dwordx4 v[32:35], v[4:5], off nt
	v_lshl_add_u64 v[4:5], v[4:5], 0, s[26:27]
	global_load_dwordx4 v[36:39], v[4:5], off nt
	v_lshl_add_u32 v6, v3, 2, s28
	v_lshlrev_b32_e32 v6, 7, v6
	v_lshl_add_u32 v6, v2, 4, v6
	v_mov_b32_e32 v7, 0
	v_lshl_add_u64 v[6:7], s[20:21], 0, v[6:7]
	s_waitcnt vmcnt(0)
	v_cvt_pk_bf16_f32 v40, v8, v12
	v_cvt_pk_bf16_f32 v41, v16, v20
	v_cvt_pk_bf16_f32 v42, v24, v28
	v_cvt_pk_bf16_f32 v43, v32, v36
	global_store_dwordx4 v[6:7], v[40:43], off sc1
	v_cvt_pk_bf16_f32 v44, v9, v13
	v_cvt_pk_bf16_f32 v45, v17, v21
	v_cvt_pk_bf16_f32 v46, v25, v29
	v_cvt_pk_bf16_f32 v47, v33, v37
	global_store_dwordx4 v[6:7], v[44:47], off offset:128 sc1
	v_cvt_pk_bf16_f32 v48, v10, v14
	v_cvt_pk_bf16_f32 v49, v18, v22
	v_cvt_pk_bf16_f32 v50, v26, v30
	v_cvt_pk_bf16_f32 v51, v34, v38
	global_store_dwordx4 v[6:7], v[48:51], off offset:256 sc1
	v_cvt_pk_bf16_f32 v52, v11, v15
	v_cvt_pk_bf16_f32 v53, v19, v23
	v_cvt_pk_bf16_f32 v54, v27, v31
	v_cvt_pk_bf16_f32 v55, v35, v39
	global_store_dwordx4 v[6:7], v[52:55], off offset:384 sc1
